# attention MODE0 loop restructured: K frags prefetched across halves, interior bias reads batched (no swap moves), V reads batched
# speedup vs baseline: 1.0168x; 1.0080x over previous
; #define LAS __attribute__((address_space(3)))
; #define MFMA32(a, b, c) __builtin_amdgcn_mfma_f32_32x32x16_bf16((a), (b), (c), 0, 0, 0)
; template <int MODE> ...
;     ...
;         { const LAS unsigned char* ka = KT + (32 * nt + ql) * KT_PITCH + 16 * half;
; #pragma unroll
;           for (int kg = 0; kg < 2; ++kg) { bf16x8 kf[4];
; #pragma unroll
;               for (int ks = 0; ks < 4; ++ks) kf[ks] = *(const LAS bf16x8*)(ka + 32 * (4 * kg + ks));
; #pragma unroll
;               for (int ks = 0; ks < 4; ++ks) st = MFMA32(kf[ks], qf[4 * kg + ks], st); } }
;     ...
;         } else {
;             const int key0 = 32 * nt + 4 * half, d0 = t - kp0 - kstride * key0, nvk = lanevalid ? nvalid - key0 : 0;
; #pragma unroll
;             for (int rg = 0; rg < 2; ++rg) { float bv[8];
; #pragma unroll
;                 for (int r8 = 0; r8 < 8; ++r8) { const int r = 8 * rg + r8; const int cr = (r & 3) + 8 * (r >> 2); const int dist = d0 - kstride * cr; bv[r8] = btab[min(max(dist, 0), 1023)]; }
; #pragma unroll
;                 for (int r8 = 0; r8 < 8; ++r8) asm volatile("" : "+v"(bv[r8]));
; #pragma unroll
;                 for (int r8 = 0; r8 < 8; ++r8) { const int r = 8 * rg + r8; const int cr = (r & 3) + 8 * (r >> 2); const int dist = d0 - kstride * cr;
;                     const bool ok = cr < nvk && (unsigned)dist < (unsigned)wlimit;
;                     const float s2 = ok ? st[r] * SC + bv[r8] : NEG_S; st[r] = s2; mloc = fmaxf(mloc, s2); } }
.LBB0_2107:
	s_lshl_b32 s26, s63, 5
	s_cmp_lg_u32 s63, 0
	s_cbranch_scc1 .Lattn_kready
	v_or_b32_e32 v16, s26, v227
	v_mad_u32_u24 v16, v16, s54, v2
	ds_read_b128 v[82:85], v16
	ds_read_b128 v[86:89], v16 offset:32
	ds_read_b128 v[90:93], v16 offset:64
	ds_read_b128 v[94:97], v16 offset:96
	ds_read_b128 v[98:101], v16 offset:128
	ds_read_b128 v[102:105], v16 offset:160
	ds_read_b128 v[106:109], v16 offset:192
	ds_read_b128 v[110:113], v16 offset:224
	s_waitcnt lgkmcnt(7)
	v_mfma_f32_32x32x16_bf16 v[146:161], v[82:85], v[166:169], 0
	s_waitcnt lgkmcnt(6)
	v_mfma_f32_32x32x16_bf16 v[146:161], v[86:89], v[162:165], v[146:161]
	s_waitcnt lgkmcnt(5)
	v_mfma_f32_32x32x16_bf16 v[146:161], v[90:93], v[174:177], v[146:161]
	s_waitcnt lgkmcnt(4)
	v_mfma_f32_32x32x16_bf16 v[146:161], v[94:97], v[170:173], v[146:161]
	s_waitcnt lgkmcnt(3)
	v_mfma_f32_32x32x16_bf16 v[146:161], v[98:101], v[182:185], v[146:161]
	s_waitcnt lgkmcnt(2)
	v_mfma_f32_32x32x16_bf16 v[146:161], v[102:105], v[178:181], v[146:161]
	s_waitcnt lgkmcnt(1)
	v_mfma_f32_32x32x16_bf16 v[146:161], v[106:109], v[190:193], v[146:161]
	s_waitcnt lgkmcnt(0)
	v_mfma_f32_32x32x16_bf16 v[146:161], v[110:113], v[186:189], v[146:161]
	s_branch .Lattn_qkdone
.Lattn_kready:
	s_waitcnt lgkmcnt(0)
	v_mfma_f32_32x32x16_bf16 v[146:161], v[82:85], v[166:169], 0
	v_mfma_f32_32x32x16_bf16 v[146:161], v[86:89], v[162:165], v[146:161]
	v_mfma_f32_32x32x16_bf16 v[146:161], v[90:93], v[174:177], v[146:161]
	v_mfma_f32_32x32x16_bf16 v[146:161], v[94:97], v[170:173], v[146:161]
	v_mfma_f32_32x32x16_bf16 v[146:161], v[98:101], v[182:185], v[146:161]
	v_mfma_f32_32x32x16_bf16 v[146:161], v[102:105], v[178:181], v[146:161]
	v_mfma_f32_32x32x16_bf16 v[146:161], v[106:109], v[190:193], v[146:161]
	v_mfma_f32_32x32x16_bf16 v[146:161], v[110:113], v[186:189], v[146:161]
.Lattn_qkdone:
	s_and_saveexec_b64 s[70:71], s[10:11]
	s_xor_b64 s[80:81], exec, s[70:71]
	s_cbranch_execz .LBB0_2113
	s_and_saveexec_b64 s[70:71], s[14:15]
	s_xor_b64 s[94:95], exec, s[70:71]
	s_cbranch_execz .LBB0_2110
	v_or_b32_e32 v16, s26, v229
	v_mad_u32_u24 v17, s25, v16, v1
	v_sub_u32_e32 v212, v230, v17
	v_add_u32_e32 v209, s44, v212
	v_add_u32_e32 v214, s96, v209
	v_subrev_u32_e32 v216, s25, v214
	v_subrev_u32_e32 v17, s25, v212
	v_subrev_u32_e32 v207, s6, v212
	v_subrev_u32_e32 v211, s7, v212
	v_subrev_u32_e32 v218, s25, v216
	v_sub_u32_e32 v219, s84, v16
	v_med3_i32 v16, v212, 0, v223
	v_med3_i32 v206, v17, 0, v223
	v_med3_i32 v208, v207, 0, v223
	v_med3_i32 v210, v209, 0, v223
	v_med3_i32 v213, v211, 0, v223
	v_med3_i32 v215, v214, 0, v223
	v_med3_i32 v217, v216, 0, v223
	v_med3_i32 v246, v218, 0, v223
	v_lshl_add_u32 v16, v16, 2, s58
	v_lshl_add_u32 v206, v206, 2, s58
	v_lshl_add_u32 v208, v208, 2, s58
	v_lshl_add_u32 v210, v210, 2, s58
	v_lshl_add_u32 v213, v213, 2, s58
	v_lshl_add_u32 v215, v215, 2, s58
	v_lshl_add_u32 v217, v217, 2, s58
	v_lshl_add_u32 v246, v246, 2, s58
	ds_read_b32 v16, v16 offset:34816
	ds_read_b32 v206, v206 offset:34816
	ds_read_b32 v208, v208 offset:34816
	ds_read_b32 v210, v210 offset:34816
	ds_read_b32 v213, v213 offset:34816
	ds_read_b32 v215, v215 offset:34816
	ds_read_b32 v217, v217 offset:34816
	ds_read_b32 v246, v246 offset:34816
	v_cmp_lt_i32_e32 vcc, 0, v219
	s_waitcnt lgkmcnt(7)
	s_and_b64 s[70:71], s[74:75], vcc
	v_cmp_gt_u32_e32 vcc, s85, v212
	v_fmac_f32_e32 v16, 0x3e0293ee, v146
	s_and_b64 vcc, s[70:71], vcc
	v_cndmask_b32_e32 v16, v224, v16, vcc
	v_cmp_lt_i32_e32 vcc, 1, v219
	s_waitcnt lgkmcnt(6)
	s_and_b64 s[70:71], s[74:75], vcc
	v_cmp_gt_u32_e32 vcc, s85, v17
	v_fmac_f32_e32 v206, 0x3e0293ee, v147
	s_and_b64 vcc, s[70:71], vcc
	v_cndmask_b32_e32 v17, v224, v206, vcc
	v_cmp_lt_i32_e32 vcc, 2, v219
	s_waitcnt lgkmcnt(5)
	s_and_b64 s[70:71], s[74:75], vcc
	v_cmp_gt_u32_e32 vcc, s85, v207
	v_fmac_f32_e32 v208, 0x3e0293ee, v148
	s_and_b64 vcc, s[70:71], vcc
	v_cndmask_b32_e32 v206, v224, v208, vcc
	v_cmp_lt_i32_e32 vcc, 3, v219
	s_waitcnt lgkmcnt(4)
	s_and_b64 s[70:71], s[74:75], vcc
	v_cmp_gt_u32_e32 vcc, s85, v209
	v_fmac_f32_e32 v210, 0x3e0293ee, v149
	s_and_b64 vcc, s[70:71], vcc
	v_cndmask_b32_e32 v207, v224, v210, vcc
	v_cmp_lt_i32_e32 vcc, 8, v219
	s_waitcnt lgkmcnt(3)
	s_and_b64 s[70:71], s[74:75], vcc
	v_cmp_gt_u32_e32 vcc, s85, v211
	v_fmac_f32_e32 v213, 0x3e0293ee, v150
	s_and_b64 vcc, s[70:71], vcc
	v_cndmask_b32_e32 v210, v224, v213, vcc
	v_cmp_lt_i32_e32 vcc, 9, v219
	s_waitcnt lgkmcnt(2)
	s_and_b64 s[70:71], s[74:75], vcc
	v_cmp_gt_u32_e32 vcc, s85, v214
	v_fmac_f32_e32 v215, 0x3e0293ee, v151
	s_and_b64 vcc, s[70:71], vcc
	v_cndmask_b32_e32 v211, v224, v215, vcc
	v_cmp_lt_i32_e32 vcc, 10, v219
	v_add_u32_e32 v149, s96, v218
	s_waitcnt lgkmcnt(1)
	s_waitcnt lgkmcnt(0)
; #define LAS __attribute__((address_space(3)))
; template <int MODE> ...
;     ...
;         } else if (interior) {
;             const LAS float* bp = btab + (t - kp0 - (32 * nt + 4 * half));
; #pragma unroll
;             for (int rg = 0; rg < 4; ++rg) { float bv[4];
; #pragma unroll
;                 for (int r4 = 0; r4 < 4; ++r4) bv[r4] = *(bp - (8 * rg + r4));
; #pragma unroll
;                 for (int r4 = 0; r4 < 4; ++r4) asm volatile("" : "+v"(bv[r4]));
; #pragma unroll
;                 for (int r4 = 0; r4 < 4; ++r4) { const int r = 4 * rg + r4; const float s2 = st[r] * SC + bv[r4]; st[r] = s2; mloc = fmaxf(mloc, s2); } }
;             if (!lanevalid) mloc = NEG_S;
;         } else {
;             const int key0 = 32 * nt + 4 * half, d0 = t - kp0 - kstride * key0, nvk = lanevalid ? nvalid - key0 : 0;
; #pragma unroll
;             for (int rg = 0; rg < 2; ++rg) { float bv[8];
; #pragma unroll
;                 for (int r8 = 0; r8 < 8; ++r8) { const int r = 8 * rg + r8; const int cr = (r & 3) + 8 * (r >> 2); const int dist = d0 - kstride * cr; bv[r8] = btab[min(max(dist, 0), 1023)]; }
; #pragma unroll
;                 for (int r8 = 0; r8 < 8; ++r8) asm volatile("" : "+v"(bv[r8]));
; #pragma unroll
;                 for (int r8 = 0; r8 < 8; ++r8) { const int r = 8 * rg + r8; const int cr = (r & 3) + 8 * (r >> 2); const int dist = d0 - kstride * cr;
;                     const bool ok = cr < nvk && (unsigned)dist < (unsigned)wlimit;
;                     const float s2 = ok ? st[r] * SC + bv[r8] : NEG_S; st[r] = s2; mloc = fmaxf(mloc, s2); } }
	s_and_b64 s[70:71], s[74:75], vcc
	v_cmp_gt_u32_e32 vcc, s85, v216
	v_subrev_u32_e32 v151, s25, v149
	v_fmac_f32_e32 v217, 0x3e0293ee, v152
	s_and_b64 vcc, s[70:71], vcc
	v_fmac_f32_e32 v246, 0x3e0293ee, v153
	v_subrev_u32_e32 v153, s25, v151
	v_cndmask_b32_e32 v208, v224, v217, vcc
	v_cmp_lt_i32_e32 vcc, 11, v219
	v_add_u32_e32 v216, s97, v153
	s_and_b64 s[70:71], s[74:75], vcc
	v_cmp_gt_u32_e32 vcc, s85, v218
	v_subrev_u32_e32 v217, s25, v216
	s_and_b64 vcc, s[70:71], vcc
	v_subrev_u32_e32 v218, s25, v217
	v_cndmask_b32_e32 v209, v224, v246, vcc
	v_subrev_u32_e32 v147, s62, v212
	v_subrev_u32_e32 v246, s25, v218
	v_med3_i32 v148, v147, 0, v223
	v_med3_i32 v150, v149, 0, v223
	v_med3_i32 v152, v151, 0, v223
	v_med3_i32 v247, v246, 0, v223
	v_lshl_add_u32 v148, v148, 2, s58
	v_lshl_add_u32 v150, v150, 2, s58
	v_lshl_add_u32 v152, v152, 2, s58
	v_med3_i32 v212, v153, 0, v223
	v_med3_i32 v213, v216, 0, v223
	v_med3_i32 v214, v217, 0, v223
	v_med3_i32 v215, v218, 0, v223
	v_lshl_add_u32 v247, v247, 2, s58
	v_lshl_add_u32 v212, v212, 2, s58
	v_lshl_add_u32 v213, v213, 2, s58
	v_lshl_add_u32 v214, v214, 2, s58
	v_lshl_add_u32 v215, v215, 2, s58
	ds_read_b32 v148, v148 offset:34816
	ds_read_b32 v150, v150 offset:34816
	ds_read_b32 v152, v152 offset:34816
	ds_read_b32 v248, v212 offset:34816
	ds_read_b32 v249, v213 offset:34816
	ds_read_b32 v250, v214 offset:34816
	ds_read_b32 v251, v215 offset:34816
	ds_read_b32 v247, v247 offset:34816
	v_cmp_lt_i32_e32 vcc, 16, v219
	s_waitcnt lgkmcnt(7)
	s_and_b64 s[70:71], s[74:75], vcc
	v_cmp_gt_u32_e32 vcc, s85, v147
	v_fmac_f32_e32 v148, 0x3e0293ee, v154
	s_and_b64 vcc, s[70:71], vcc
	v_cndmask_b32_e32 v212, v224, v148, vcc
	v_cmp_lt_i32_e32 vcc, 17, v219
	s_waitcnt lgkmcnt(6)
	s_and_b64 s[70:71], s[74:75], vcc
	v_cmp_gt_u32_e32 vcc, s85, v149
	v_fmac_f32_e32 v150, 0x3e0293ee, v155
	s_and_b64 vcc, s[70:71], vcc
	v_cndmask_b32_e32 v213, v224, v150, vcc
	v_cmp_lt_i32_e32 vcc, 18, v219
	s_waitcnt lgkmcnt(5)
	s_and_b64 s[70:71], s[74:75], vcc
	v_cmp_gt_u32_e32 vcc, s85, v151
	v_fmac_f32_e32 v152, 0x3e0293ee, v156
	s_and_b64 vcc, s[70:71], vcc
	v_cndmask_b32_e32 v214, v224, v152, vcc
	v_cmp_lt_i32_e32 vcc, 19, v219
	s_waitcnt lgkmcnt(4)
	s_and_b64 s[70:71], s[74:75], vcc
	v_cmp_gt_u32_e32 vcc, s85, v153
	v_fmac_f32_e32 v248, 0x3e0293ee, v157
	s_and_b64 vcc, s[70:71], vcc
	v_cndmask_b32_e32 v215, v224, v248, vcc
	v_cmp_lt_i32_e32 vcc, 24, v219
	s_waitcnt lgkmcnt(3)
	s_and_b64 s[70:71], s[74:75], vcc
	v_cmp_gt_u32_e32 vcc, s85, v216
	v_fmac_f32_e32 v249, 0x3e0293ee, v158
	s_and_b64 vcc, s[70:71], vcc
	v_cndmask_b32_e32 v216, v224, v249, vcc
	v_cmp_lt_i32_e32 vcc, 25, v219
	s_waitcnt lgkmcnt(2)
	s_and_b64 s[70:71], s[74:75], vcc
	v_cmp_gt_u32_e32 vcc, s85, v217
	v_fmac_f32_e32 v250, 0x3e0293ee, v159
	s_and_b64 vcc, s[70:71], vcc
	v_max3_f32 v146, v16, s55, v17
	v_cndmask_b32_e32 v217, v224, v250, vcc
	v_cmp_lt_i32_e32 vcc, 26, v219
	v_max3_f32 v146, v146, v206, v207
	s_waitcnt lgkmcnt(1)
	s_and_b64 s[70:71], s[74:75], vcc
	v_cmp_gt_u32_e32 vcc, s85, v218
	v_max3_f32 v146, v146, v210, v211
	v_fmac_f32_e32 v251, 0x3e0293ee, v160
	s_and_b64 vcc, s[70:71], vcc
	v_max3_f32 v146, v146, v208, v209
	v_cndmask_b32_e32 v218, v224, v251, vcc
	v_cmp_lt_i32_e32 vcc, 27, v219
	s_waitcnt lgkmcnt(0)
	v_max3_f32 v146, v146, v212, v213
	s_and_b64 s[70:71], s[74:75], vcc
	v_cmp_gt_u32_e32 vcc, s85, v246
	v_max3_f32 v146, v146, v214, v215
	v_fmac_f32_e32 v247, 0x3e0293ee, v161
	s_and_b64 vcc, s[70:71], vcc
	v_max3_f32 v146, v146, v216, v217
	v_cndmask_b32_e32 v219, v224, v247, vcc
	v_max3_f32 v246, v146, v218, v219
.LBB0_2110:
	s_andn2_saveexec_b64 s[94:95], s[94:95]
	s_cbranch_execz .LBB0_2112
	v_add_u32_e32 v16, s26, v242
	v_sub_u32_e32 v16, v228, v16
	v_lshl_add_u32 v216, v16, 2, s58
	v_add_u32_e32 v216, 0x8794, v216
	ds_read2_b32 v[114:115], v216 offset0:26 offset1:27
	ds_read2_b32 v[116:117], v216 offset0:24 offset1:25
	ds_read2_b32 v[118:119], v216 offset0:18 offset1:19
	ds_read2_b32 v[120:121], v216 offset0:16 offset1:17
	ds_read2_b32 v[122:123], v216 offset0:10 offset1:11
	ds_read2_b32 v[124:125], v216 offset0:8 offset1:9
	ds_read2_b32 v[126:127], v216 offset0:2 offset1:3
	ds_read2_b32 v[128:129], v216 offset0:0 offset1:1
	s_waitcnt lgkmcnt(7)
	v_pk_fma_f32 v[16:17], v[146:147], s[82:83], v[114:115] op_sel:[0,0,1] op_sel_hi:[1,0,0]
	s_waitcnt lgkmcnt(6)
	v_pk_fma_f32 v[206:207], v[148:149], s[82:83], v[116:117] op_sel:[0,0,1] op_sel_hi:[1,0,0]
	s_waitcnt lgkmcnt(5)
	v_pk_fma_f32 v[210:211], v[150:151], s[82:83], v[118:119] op_sel:[0,0,1] op_sel_hi:[1,0,0]
	v_max3_f32 v146, v16, s55, v17
	s_waitcnt lgkmcnt(4)
	v_pk_fma_f32 v[208:209], v[152:153], s[82:83], v[120:121] op_sel:[0,0,1] op_sel_hi:[1,0,0]
	v_max3_f32 v146, v146, v206, v207
	s_waitcnt lgkmcnt(3)
	v_pk_fma_f32 v[212:213], v[154:155], s[82:83], v[122:123] op_sel:[0,0,1] op_sel_hi:[1,0,0]
	v_max3_f32 v146, v146, v210, v211
	s_waitcnt lgkmcnt(2)
	v_pk_fma_f32 v[214:215], v[156:157], s[82:83], v[124:125] op_sel:[0,0,1] op_sel_hi:[1,0,0]
	v_max3_f32 v146, v146, v208, v209
	s_waitcnt lgkmcnt(1)
	v_pk_fma_f32 v[216:217], v[158:159], s[82:83], v[126:127] op_sel:[0,0,1] op_sel_hi:[1,0,0]
	v_max3_f32 v146, v146, v212, v213
	s_waitcnt lgkmcnt(0)
	v_pk_fma_f32 v[218:219], v[160:161], s[82:83], v[128:129] op_sel:[0,0,1] op_sel_hi:[1,0,0]
	v_max3_f32 v146, v146, v214, v215
	v_max3_f32 v146, v146, v216, v217
	v_max3_f32 v146, v146, v218, v219
	v_cndmask_b32_e64 v246, v224, v146, s[74:75]

; #define LAS __attribute__((address_space(3)))
; __device__ __forceinline__ unsigned pk2(float lo, float hi) { const bfx2 b = __builtin_convertvector((f32x2){lo, hi}, bfx2); return __builtin_bit_cast(unsigned, b); }
; #define MFMA32(a, b, c) __builtin_amdgcn_mfma_f32_32x32x16_bf16((a), (b), (c), 0, 0, 0)
; template <int MODE> ...
;     ...
;         { const LAS unsigned char* ka = KT + (32 * nt + ql) * KT_PITCH + 16 * half;
; #pragma unroll
;           for (int kg = 0; kg < 2; ++kg) { bf16x8 kf[4];
; #pragma unroll
;               for (int ks = 0; ks < 4; ++ks) kf[ks] = *(const LAS bf16x8*)(ka + 32 * (4 * kg + ks));
;     ...
;             float ls = 0.f; const float meff = lanevalid ? m : 3.0e30f;
; #pragma unroll
;             for (int r = 0; r < 16; ++r) { const float pv = __builtin_amdgcn_exp2f(st[r] - meff); st[r] = pv; ls += pv; }
;             l += ls;
; #pragma unroll
;             for (int s = 0; s < 2; ++s) {
;                 u32x4 pb; pb.x = pk2(st[8 * s + 0], st[8 * s + 1]); pb.y = pk2(st[8 * s + 2], st[8 * s + 3]); pb.z = pk2(st[8 * s + 4], st[8 * s + 5]); pb.w = pk2(st[8 * s + 6], st[8 * s + 7]);
;                 const bf16x8 bfrag = __builtin_bit_cast(bf16x8, pb);
;                 const LAS unsigned char* va = VT + ql * VT_PITCH + (32 * nt + 16 * s + 4 * half) * 2;
;                 s16x4 lo[4], hi[4];
; #pragma unroll
;                 for (int dt = 0; dt < 4; ++dt) { lo[dt] = *(const LAS s16x4*)(va + 32 * dt * VT_PITCH); hi[dt] = *(const LAS s16x4*)(va + 32 * dt * VT_PITCH + 16); }
; #pragma unroll
;                 for (int dt = 0; dt < 4; ++dt) { const bf16x8 afrag = __builtin_shufflevector(lo[dt], hi[dt], 0, 1, 2, 3, 4, 5, 6, 7); ot[dt] = MFMA32(afrag, bfrag, ot[dt]); }
;             }
.LBB0_2118:
	v_cndmask_b32_e64 v147, v225, v146, s[74:75]
	v_lshl_add_u32 v159, s63, 6, v244
	v_add_u32_e32 v156, 0x4000, v159
	v_add_u32_e32 v157, 0x5000, v159
	v_add_u32_e32 v158, 0x6000, v159
	v_add_u32_e32 v159, 0x7000, v159
	ds_read2_b64 v[114:117], v156 offset0:128 offset1:130
	ds_read2_b64 v[118:121], v157 offset0:160 offset1:162
	ds_read2_b64 v[122:125], v158 offset0:192 offset1:194
	ds_read2_b64 v[126:129], v159 offset0:224 offset1:226
	ds_read2_b64 v[130:133], v156 offset0:132 offset1:134
	ds_read2_b64 v[134:137], v157 offset0:164 offset1:166
	ds_read2_b64 v[138:141], v158 offset0:196 offset1:198
	ds_read2_b64 v[142:145], v159 offset0:228 offset1:230
	v_sub_f32_e32 v16, v16, v147
	v_sub_f32_e32 v17, v17, v147
	v_sub_f32_e32 v206, v206, v147
	v_sub_f32_e32 v207, v207, v147
	v_sub_f32_e32 v210, v210, v147
	v_sub_f32_e32 v211, v211, v147
	v_sub_f32_e32 v208, v208, v147
	v_sub_f32_e32 v209, v209, v147
	v_exp_f32_e32 v16, v16
	v_exp_f32_e32 v17, v17
	v_exp_f32_e32 v206, v206
	v_exp_f32_e32 v207, v207
	v_exp_f32_e32 v210, v210
	v_exp_f32_e32 v211, v211
	v_exp_f32_e32 v208, v208
	v_exp_f32_e32 v209, v209
	v_sub_f32_e32 v212, v212, v147
	v_cvt_pk_bf16_f32 v152, v16, v17
	v_cvt_pk_bf16_f32 v153, v206, v207
	v_cvt_pk_bf16_f32 v154, v210, v211
	v_cvt_pk_bf16_f32 v155, v208, v209
	v_sub_f32_e32 v213, v213, v147
	v_exp_f32_e32 v212, v212
	s_waitcnt lgkmcnt(7)
	v_mfma_f32_32x32x16_bf16 v[66:81], v[114:117], v[152:155], v[66:81]
	v_exp_f32_e32 v213, v213
	v_sub_f32_e32 v214, v214, v147
	v_exp_f32_e32 v214, v214
	v_sub_f32_e32 v215, v215, v147
	s_waitcnt lgkmcnt(6)
	v_mfma_f32_32x32x16_bf16 v[50:65], v[118:121], v[152:155], v[50:65]
	v_exp_f32_e32 v215, v215
	v_sub_f32_e32 v216, v216, v147
	v_exp_f32_e32 v216, v216
	v_sub_f32_e32 v217, v217, v147
	s_waitcnt lgkmcnt(5)
	v_mfma_f32_32x32x16_bf16 v[34:49], v[122:125], v[152:155], v[34:49]
	v_exp_f32_e32 v217, v217
	v_sub_f32_e32 v218, v218, v147
	v_exp_f32_e32 v218, v218
	v_sub_f32_e32 v219, v219, v147
	s_waitcnt lgkmcnt(4)
	v_mfma_f32_32x32x16_bf16 v[18:33], v[126:129], v[152:155], v[18:33]
	v_exp_f32_e32 v219, v219
	v_add_f32_e32 v16, 0, v16
	v_cvt_pk_bf16_f32 v148, v212, v213
	v_cvt_pk_bf16_f32 v149, v214, v215
	v_cvt_pk_bf16_f32 v150, v216, v217
	s_cmp_lg_u32 s63, 0
	s_cbranch_scc1 .Lattn_tail_b
	v_or_b32_e32 v160, 32, v227
	v_mad_u32_u24 v160, v160, s54, v2
	ds_read_b128 v[82:85], v160
	ds_read_b128 v[86:89], v160 offset:32
	ds_read_b128 v[90:93], v160 offset:64
	ds_read_b128 v[94:97], v160 offset:96
	ds_read_b128 v[98:101], v160 offset:128
	ds_read_b128 v[102:105], v160 offset:160
	ds_read_b128 v[106:109], v160 offset:192
	ds_read_b128 v[110:113], v160 offset:224
	v_add_f32_e32 v16, v17, v16
	v_add_f32_e32 v16, v206, v16
	v_cvt_pk_bf16_f32 v151, v218, v219
	v_add_f32_e32 v16, v207, v16
	v_add_f32_e32 v16, v210, v16
	s_waitcnt lgkmcnt(11)
	v_mfma_f32_32x32x16_bf16 v[66:81], v[130:133], v[148:151], v[66:81]
	v_add_f32_e32 v16, v211, v16
	v_add_f32_e32 v16, v208, v16
	v_add_f32_e32 v16, v209, v16
	v_add_f32_e32 v16, v212, v16
	s_waitcnt lgkmcnt(10)
	v_mfma_f32_32x32x16_bf16 v[50:65], v[134:137], v[148:151], v[50:65]
	v_add_f32_e32 v16, v213, v16
	v_add_f32_e32 v16, v214, v16
	v_add_f32_e32 v16, v215, v16
	v_add_f32_e32 v16, v216, v16
	s_waitcnt lgkmcnt(9)
	v_mfma_f32_32x32x16_bf16 v[34:49], v[138:141], v[148:151], v[34:49]
	v_add_f32_e32 v16, v217, v16
	v_add_f32_e32 v16, v218, v16
	v_add_f32_e32 v16, v219, v16
	v_add_f32_e32 v243, v243, v16
	s_xor_b64 s[26:27], s[46:47], -1
	s_mov_b32 s63, 1
	s_andn2_b64 vcc, exec, s[26:27]
	s_mov_b64 s[46:47], 0
	s_waitcnt lgkmcnt(8)
	v_mfma_f32_32x32x16_bf16 v[18:33], v[142:145], v[148:151], v[18:33]
	v_mov_b32_e32 v245, v146
	s_branch .LBB0_2107
.Lattn_tail_b:
	v_add_f32_e32 v16, v17, v16
	v_add_f32_e32 v16, v206, v16
	v_cvt_pk_bf16_f32 v151, v218, v219
	v_add_f32_e32 v16, v207, v16
	v_add_f32_e32 v16, v210, v16
	s_waitcnt lgkmcnt(3)
	v_mfma_f32_32x32x16_bf16 v[66:81], v[130:133], v[148:151], v[66:81]
	v_add_f32_e32 v16, v211, v16
	v_add_f32_e32 v16, v208, v16
	v_add_f32_e32 v16, v209, v16
	v_add_f32_e32 v16, v212, v16
	s_waitcnt lgkmcnt(2)
	v_mfma_f32_32x32x16_bf16 v[50:65], v[134:137], v[148:151], v[50:65]
	v_add_f32_e32 v16, v213, v16
	v_add_f32_e32 v16, v214, v16
	v_add_f32_e32 v16, v215, v16
	v_add_f32_e32 v16, v216, v16
	s_waitcnt lgkmcnt(1)
	v_mfma_f32_32x32x16_bf16 v[34:49], v[138:141], v[148:151], v[34:49]
	v_add_f32_e32 v16, v217, v16
	v_add_f32_e32 v16, v218, v16
	v_add_f32_e32 v16, v219, v16
	v_add_f32_e32 v243, v243, v16
	s_xor_b64 s[26:27], s[46:47], -1
	s_mov_b32 s63, 1
	s_andn2_b64 vcc, exec, s[26:27]
	s_mov_b64 s[46:47], 0
	s_waitcnt lgkmcnt(0)
	v_mfma_f32_32x32x16_bf16 v[18:33], v[142:145], v[148:151], v[18:33]
	s_branch .Lattn_m0_exit
